# saddr LDS-DMA in all K-loops + batched residual loads (all 16 up front, counted vmcnt, global ops) in P13 and P16 epilogues
# speedup vs baseline: 1.0125x; 1.0060x over previous
; __device__ __forceinline__ float bf_lo(unsigned u) { return __uint_as_float(u << 16); }
; __device__ __forceinline__ float bf_hi(unsigned u) { return __uint_as_float(u & 0xffff0000u); }
;     __device__ __forceinline__ void operator()(AccRef acc, const Unit& u, int wr, int wc, int fr, int fq) const {
;         const int row0 = u.pm * BM + wr * 64 + fr, col0 = u.pn * BM + wc * 32 + 8 * fq;
; #pragma unroll
;         for (int ai = 0; ai < 2; ++ai)
; #pragma unroll
;             for (int m = 0; m < 4; ++m) {
;                 const size_t off = (size_t)(row0 + ai * HALF + m * 16) * D + col0;
; #pragma unroll
;                 for (int bj = 0; bj < 2; ++bj) {
;                     const u32x4 hv = *(const u32x4*)(hb + off + bj * HALF);
;                     f32x4 r0, r1;
;                     r0[0] = bf_lo(hv.x); r0[1] = bf_hi(hv.x); r0[2] = bf_lo(hv.y); r0[3] = bf_hi(hv.y); r1[0] = bf_lo(hv.z); r1[1] = bf_hi(hv.z); r1[2] = bf_lo(hv.w); r1[3] = bf_hi(hv.w);
;                     *(f32x4*)(out + off + bj * HALF) = r0 * alpha + acc[ai][bj][m][0] * s;
;                     *(f32x4*)(out + off + bj * HALF + 4) = r1 * alpha + acc[ai][bj][m][1] * s;
;                 }
;                 if (m == 3) asm volatile("" ::: "memory");
;             }
;     }
.LBB0_784:
	v_mov_b32_e32 v144, v147
	v_mov_b32_e32 v145, v146
	s_lshl_b32 s29, s38, 8
	s_add_i32 s29, s29, s57
	v_add_u32_e32 v144, s29, v144
	s_lshl_b32 s29, s64, 8
	s_or_b32 s29, s29, s58
	v_lshl_add_u32 v152, v145, 3, s29
	v_ashrrev_i32_e32 v145, 31, v144
	v_ashrrev_i32_e32 v153, 31, v152
	v_lshlrev_b64 v[144:145], 11, v[144:145]
	v_lshl_add_u64 v[144:145], v[144:145], 0, v[152:153]
	s_andn2_b64 vcc, exec, s[0:1]
	s_mov_b64 s[0:1], -1
	v_lshl_add_u64 v[238:239], v[144:145], 1, s[6:7]
	global_load_dwordx4 v[160:163], v[238:239], off
	global_load_dwordx4 v[164:167], v[238:239], off offset:256
	v_lshl_add_u64 v[224:225], v[144:145], 0, s[14:15]
	v_lshl_add_u64 v[240:241], v[224:225], 1, s[6:7]
	global_load_dwordx4 v[168:171], v[240:241], off
	global_load_dwordx4 v[172:175], v[240:241], off offset:256
	v_lshl_add_u64 v[226:227], v[144:145], 0, s[16:17]
	v_lshl_add_u64 v[242:243], v[226:227], 1, s[6:7]
	global_load_dwordx4 v[176:179], v[242:243], off
	global_load_dwordx4 v[180:183], v[242:243], off offset:256
	v_lshl_add_u64 v[228:229], v[144:145], 0, s[18:19]
	v_lshl_add_u64 v[244:245], v[228:229], 1, s[6:7]
	global_load_dwordx4 v[184:187], v[244:245], off
	global_load_dwordx4 v[188:191], v[244:245], off offset:256
	v_lshl_add_u64 v[230:231], v[144:145], 0, s[20:21]
	v_lshl_add_u64 v[246:247], v[230:231], 1, s[6:7]
	global_load_dwordx4 v[192:195], v[246:247], off
	global_load_dwordx4 v[196:199], v[246:247], off offset:256
	v_lshl_add_u64 v[232:233], v[144:145], 0, s[22:23]
	v_lshl_add_u64 v[248:249], v[232:233], 1, s[6:7]
	global_load_dwordx4 v[200:203], v[248:249], off
	global_load_dwordx4 v[204:207], v[248:249], off offset:256
	v_lshl_add_u64 v[234:235], v[144:145], 0, s[24:25]
	v_lshl_add_u64 v[250:251], v[234:235], 1, s[6:7]
	global_load_dwordx4 v[208:211], v[250:251], off
	global_load_dwordx4 v[212:215], v[250:251], off offset:256
	v_lshl_add_u64 v[236:237], v[144:145], 0, s[26:27]
	v_lshl_add_u64 v[252:253], v[236:237], 1, s[6:7]
	global_load_dwordx4 v[216:219], v[252:253], off
	global_load_dwordx4 v[220:223], v[252:253], off offset:256
	v_lshl_add_u64 v[152:153], v[144:145], 2, s[2:3]
	s_waitcnt vmcnt(15)
	v_lshlrev_b32_e32 v156, 16, v160
	v_and_b32_e32 v157, 0xffff0000, v160
	v_lshlrev_b32_e32 v160, 16, v161
	v_and_b32_e32 v161, 0xffff0000, v161
	v_lshlrev_b32_e32 v158, 16, v162
	v_and_b32_e32 v159, 0xffff0000, v162
	v_lshlrev_b32_e32 v162, 16, v163
	v_and_b32_e32 v163, 0xffff0000, v163
	v_pk_fma_f32 v[126:127], v[160:161], s[12:13], v[126:127] op_sel_hi:[1,0,1]
	v_pk_fma_f32 v[124:125], v[156:157], s[12:13], v[124:125] op_sel_hi:[1,0,1]
	v_pk_fma_f32 v[122:123], v[162:163], s[12:13], v[122:123] op_sel_hi:[1,0,1]
	v_pk_fma_f32 v[120:121], v[158:159], s[12:13], v[120:121] op_sel_hi:[1,0,1]
	global_store_dwordx4 v[152:153], v[124:127], off
	global_store_dwordx4 v[152:153], v[120:123], off offset:16
	s_waitcnt vmcnt(16)
	v_lshlrev_b32_e32 v156, 16, v164
	v_and_b32_e32 v157, 0xffff0000, v164
	v_lshlrev_b32_e32 v164, 16, v165
	v_and_b32_e32 v165, 0xffff0000, v165
	v_lshlrev_b32_e32 v158, 16, v166
	v_and_b32_e32 v159, 0xffff0000, v166
	v_lshlrev_b32_e32 v166, 16, v167
	v_and_b32_e32 v167, 0xffff0000, v167
	v_pk_fma_f32 v[118:119], v[164:165], s[12:13], v[118:119] op_sel_hi:[1,0,1]
	v_pk_fma_f32 v[116:117], v[156:157], s[12:13], v[116:117] op_sel_hi:[1,0,1]
	v_pk_fma_f32 v[114:115], v[166:167], s[12:13], v[114:115] op_sel_hi:[1,0,1]
	v_pk_fma_f32 v[112:113], v[158:159], s[12:13], v[112:113] op_sel_hi:[1,0,1]
	global_store_dwordx4 v[152:153], v[116:119], off offset:512
	global_store_dwordx4 v[152:153], v[112:115], off offset:528
	v_lshl_add_u64 v[154:155], v[224:225], 2, s[2:3]
	s_waitcnt vmcnt(17)
	v_lshlrev_b32_e32 v156, 16, v168
	v_and_b32_e32 v157, 0xffff0000, v168
	v_lshlrev_b32_e32 v168, 16, v169
	v_and_b32_e32 v169, 0xffff0000, v169
	v_lshlrev_b32_e32 v158, 16, v170
	v_and_b32_e32 v159, 0xffff0000, v170
	v_lshlrev_b32_e32 v170, 16, v171
	v_and_b32_e32 v171, 0xffff0000, v171
	v_pk_fma_f32 v[110:111], v[168:169], s[12:13], v[110:111] op_sel_hi:[1,0,1]
	v_pk_fma_f32 v[108:109], v[156:157], s[12:13], v[108:109] op_sel_hi:[1,0,1]
	v_pk_fma_f32 v[106:107], v[170:171], s[12:13], v[106:107] op_sel_hi:[1,0,1]
	v_pk_fma_f32 v[104:105], v[158:159], s[12:13], v[104:105] op_sel_hi:[1,0,1]
	global_store_dwordx4 v[154:155], v[108:111], off
	global_store_dwordx4 v[154:155], v[104:107], off offset:16
	s_waitcnt vmcnt(18)
	v_lshlrev_b32_e32 v156, 16, v172
	v_and_b32_e32 v157, 0xffff0000, v172
	v_lshlrev_b32_e32 v172, 16, v173
	v_and_b32_e32 v173, 0xffff0000, v173
	v_lshlrev_b32_e32 v158, 16, v174
	v_and_b32_e32 v159, 0xffff0000, v174
	v_lshlrev_b32_e32 v174, 16, v175
	v_and_b32_e32 v175, 0xffff0000, v175
	v_pk_fma_f32 v[102:103], v[172:173], s[12:13], v[102:103] op_sel_hi:[1,0,1]
	v_pk_fma_f32 v[100:101], v[156:157], s[12:13], v[100:101] op_sel_hi:[1,0,1]
	v_pk_fma_f32 v[98:99], v[174:175], s[12:13], v[98:99] op_sel_hi:[1,0,1]
	v_pk_fma_f32 v[96:97], v[158:159], s[12:13], v[96:97] op_sel_hi:[1,0,1]
	global_store_dwordx4 v[154:155], v[100:103], off offset:512
	global_store_dwordx4 v[154:155], v[96:99], off offset:528
	v_lshl_add_u64 v[152:153], v[226:227], 2, s[2:3]
	s_waitcnt vmcnt(19)
	v_lshlrev_b32_e32 v156, 16, v176
	v_and_b32_e32 v157, 0xffff0000, v176
	v_lshlrev_b32_e32 v176, 16, v177
	v_and_b32_e32 v177, 0xffff0000, v177
	v_lshlrev_b32_e32 v158, 16, v178
	v_and_b32_e32 v159, 0xffff0000, v178
	v_lshlrev_b32_e32 v178, 16, v179
	v_and_b32_e32 v179, 0xffff0000, v179
	v_pk_fma_f32 v[94:95], v[176:177], s[12:13], v[94:95] op_sel_hi:[1,0,1]
	v_pk_fma_f32 v[92:93], v[156:157], s[12:13], v[92:93] op_sel_hi:[1,0,1]
	v_pk_fma_f32 v[90:91], v[178:179], s[12:13], v[90:91] op_sel_hi:[1,0,1]
	v_pk_fma_f32 v[88:89], v[158:159], s[12:13], v[88:89] op_sel_hi:[1,0,1]
	global_store_dwordx4 v[152:153], v[92:95], off
	global_store_dwordx4 v[152:153], v[88:91], off offset:16
	s_waitcnt vmcnt(20)
; __device__ __forceinline__ float bf_lo(unsigned u) { return __uint_as_float(u << 16); }
; __device__ __forceinline__ float bf_hi(unsigned u) { return __uint_as_float(u & 0xffff0000u); }
;     __device__ __forceinline__ void operator()(AccRef acc, const Unit& u, int wr, int wc, int fr, int fq) const {
;         const int row0 = u.pm * BM + wr * 64 + fr, col0 = u.pn * BM + wc * 32 + 8 * fq;
; #pragma unroll
;         for (int ai = 0; ai < 2; ++ai)
; #pragma unroll
;             for (int m = 0; m < 4; ++m) {
;                 const size_t off = (size_t)(row0 + ai * HALF + m * 16) * D + col0;
; #pragma unroll
;                 for (int bj = 0; bj < 2; ++bj) {
;                     const u32x4 hv = *(const u32x4*)(hb + off + bj * HALF);
;                     f32x4 r0, r1;
;                     r0[0] = bf_lo(hv.x); r0[1] = bf_hi(hv.x); r0[2] = bf_lo(hv.y); r0[3] = bf_hi(hv.y); r1[0] = bf_lo(hv.z); r1[1] = bf_hi(hv.z); r1[2] = bf_lo(hv.w); r1[3] = bf_hi(hv.w);
;                     *(f32x4*)(out + off + bj * HALF) = r0 * alpha + acc[ai][bj][m][0] * s;
;                     *(f32x4*)(out + off + bj * HALF + 4) = r1 * alpha + acc[ai][bj][m][1] * s;
;                 }
;                 if (m == 3) asm volatile("" ::: "memory");
;             }
;     }
	v_lshlrev_b32_e32 v156, 16, v180
	v_and_b32_e32 v157, 0xffff0000, v180
	v_lshlrev_b32_e32 v180, 16, v181
	v_and_b32_e32 v181, 0xffff0000, v181
	v_lshlrev_b32_e32 v158, 16, v182
	v_and_b32_e32 v159, 0xffff0000, v182
	v_lshlrev_b32_e32 v182, 16, v183
	v_and_b32_e32 v183, 0xffff0000, v183
	v_pk_fma_f32 v[86:87], v[180:181], s[12:13], v[86:87] op_sel_hi:[1,0,1]
	v_pk_fma_f32 v[84:85], v[156:157], s[12:13], v[84:85] op_sel_hi:[1,0,1]
	v_pk_fma_f32 v[82:83], v[182:183], s[12:13], v[82:83] op_sel_hi:[1,0,1]
	v_pk_fma_f32 v[80:81], v[158:159], s[12:13], v[80:81] op_sel_hi:[1,0,1]
	global_store_dwordx4 v[152:153], v[84:87], off offset:512
	global_store_dwordx4 v[152:153], v[80:83], off offset:528
	v_lshl_add_u64 v[154:155], v[228:229], 2, s[2:3]
	s_waitcnt vmcnt(21)
	v_lshlrev_b32_e32 v156, 16, v184
	v_and_b32_e32 v157, 0xffff0000, v184
	v_lshlrev_b32_e32 v184, 16, v185
	v_and_b32_e32 v185, 0xffff0000, v185
	v_lshlrev_b32_e32 v158, 16, v186
	v_and_b32_e32 v159, 0xffff0000, v186
	v_lshlrev_b32_e32 v186, 16, v187
	v_and_b32_e32 v187, 0xffff0000, v187
	v_pk_fma_f32 v[78:79], v[184:185], s[12:13], v[78:79] op_sel_hi:[1,0,1]
	v_pk_fma_f32 v[76:77], v[156:157], s[12:13], v[76:77] op_sel_hi:[1,0,1]
	v_pk_fma_f32 v[74:75], v[186:187], s[12:13], v[74:75] op_sel_hi:[1,0,1]
	v_pk_fma_f32 v[72:73], v[158:159], s[12:13], v[72:73] op_sel_hi:[1,0,1]
	global_store_dwordx4 v[154:155], v[76:79], off
	global_store_dwordx4 v[154:155], v[72:75], off offset:16
	s_waitcnt vmcnt(22)
	v_lshlrev_b32_e32 v156, 16, v188
	v_and_b32_e32 v157, 0xffff0000, v188
	v_lshlrev_b32_e32 v188, 16, v189
	v_and_b32_e32 v189, 0xffff0000, v189
	v_lshlrev_b32_e32 v158, 16, v190
	v_and_b32_e32 v159, 0xffff0000, v190
	v_lshlrev_b32_e32 v190, 16, v191
	v_and_b32_e32 v191, 0xffff0000, v191
	v_pk_fma_f32 v[70:71], v[188:189], s[12:13], v[70:71] op_sel_hi:[1,0,1]
	v_pk_fma_f32 v[68:69], v[156:157], s[12:13], v[68:69] op_sel_hi:[1,0,1]
	v_pk_fma_f32 v[66:67], v[190:191], s[12:13], v[66:67] op_sel_hi:[1,0,1]
	v_pk_fma_f32 v[64:65], v[158:159], s[12:13], v[64:65] op_sel_hi:[1,0,1]
	global_store_dwordx4 v[154:155], v[68:71], off offset:512
	global_store_dwordx4 v[154:155], v[64:67], off offset:528
	v_lshl_add_u64 v[152:153], v[230:231], 2, s[2:3]
	s_waitcnt vmcnt(23)
	v_lshlrev_b32_e32 v156, 16, v192
	v_and_b32_e32 v157, 0xffff0000, v192
	v_lshlrev_b32_e32 v192, 16, v193
	v_and_b32_e32 v193, 0xffff0000, v193
	v_lshlrev_b32_e32 v158, 16, v194
	v_and_b32_e32 v159, 0xffff0000, v194
	v_lshlrev_b32_e32 v194, 16, v195
	v_and_b32_e32 v195, 0xffff0000, v195
	v_pk_fma_f32 v[62:63], v[192:193], s[12:13], v[62:63] op_sel_hi:[1,0,1]
	v_pk_fma_f32 v[60:61], v[156:157], s[12:13], v[60:61] op_sel_hi:[1,0,1]
	v_pk_fma_f32 v[58:59], v[194:195], s[12:13], v[58:59] op_sel_hi:[1,0,1]
	v_pk_fma_f32 v[56:57], v[158:159], s[12:13], v[56:57] op_sel_hi:[1,0,1]
	global_store_dwordx4 v[152:153], v[60:63], off
	global_store_dwordx4 v[152:153], v[56:59], off offset:16
	s_waitcnt vmcnt(24)
	v_lshlrev_b32_e32 v156, 16, v196
	v_and_b32_e32 v157, 0xffff0000, v196
	v_lshlrev_b32_e32 v196, 16, v197
	v_and_b32_e32 v197, 0xffff0000, v197
	v_lshlrev_b32_e32 v158, 16, v198
	v_and_b32_e32 v159, 0xffff0000, v198
	v_lshlrev_b32_e32 v198, 16, v199
	v_and_b32_e32 v199, 0xffff0000, v199
	v_pk_fma_f32 v[54:55], v[196:197], s[12:13], v[54:55] op_sel_hi:[1,0,1]
	v_pk_fma_f32 v[52:53], v[156:157], s[12:13], v[52:53] op_sel_hi:[1,0,1]
	v_pk_fma_f32 v[50:51], v[198:199], s[12:13], v[50:51] op_sel_hi:[1,0,1]
	v_pk_fma_f32 v[48:49], v[158:159], s[12:13], v[48:49] op_sel_hi:[1,0,1]
	global_store_dwordx4 v[152:153], v[52:55], off offset:512
	global_store_dwordx4 v[152:153], v[48:51], off offset:528
	v_lshl_add_u64 v[154:155], v[232:233], 2, s[2:3]
	s_waitcnt vmcnt(25)
	v_lshlrev_b32_e32 v156, 16, v200
	v_and_b32_e32 v157, 0xffff0000, v200
	v_lshlrev_b32_e32 v200, 16, v201
	v_and_b32_e32 v201, 0xffff0000, v201
	v_lshlrev_b32_e32 v158, 16, v202
	v_and_b32_e32 v159, 0xffff0000, v202
	v_lshlrev_b32_e32 v202, 16, v203
	v_and_b32_e32 v203, 0xffff0000, v203
	v_pk_fma_f32 v[46:47], v[200:201], s[12:13], v[46:47] op_sel_hi:[1,0,1]
	v_pk_fma_f32 v[44:45], v[156:157], s[12:13], v[44:45] op_sel_hi:[1,0,1]
	v_pk_fma_f32 v[42:43], v[202:203], s[12:13], v[42:43] op_sel_hi:[1,0,1]
	v_pk_fma_f32 v[40:41], v[158:159], s[12:13], v[40:41] op_sel_hi:[1,0,1]
	global_store_dwordx4 v[154:155], v[44:47], off
	global_store_dwordx4 v[154:155], v[40:43], off offset:16
	s_waitcnt vmcnt(26)
; __device__ __forceinline__ float bf_lo(unsigned u) { return __uint_as_float(u << 16); }
; __device__ __forceinline__ float bf_hi(unsigned u) { return __uint_as_float(u & 0xffff0000u); }
; #define PG8_BAR __builtin_amdgcn_s_barrier()
; template <class Epi>
; __device__ __forceinline__ void gemm_phase(ldsp lds, const Gemm g, const StaticOrder& S, const Epi& E, int wave0) {
;     ...
;         if (!has_next) break;
; #pragma unroll
;         for (int a = 0; a < 2; ++a)
; #pragma unroll
;             for (int b = 0; b < 2; ++b)
; #pragma unroll
;                 for (int m = 0; m < 4; ++m)
; #pragma unroll
;                     for (int n = 0; n < 2; ++n) acc[a][b][m][n] = (f32x4){0.f, 0.f, 0.f, 0.f};
;         cur = nxt; cA = nA; cB = nB; ++ui;
;         if (wr == 1) PG8_BAR;
;     __device__ __forceinline__ void operator()(AccRef acc, const Unit& u, int wr, int wc, int fr, int fq) const {
;         const int row0 = u.pm * BM + wr * 64 + fr, col0 = u.pn * BM + wc * 32 + 8 * fq;
; #pragma unroll
;         for (int ai = 0; ai < 2; ++ai)
; #pragma unroll
;             for (int m = 0; m < 4; ++m) {
;                 const size_t off = (size_t)(row0 + ai * HALF + m * 16) * D + col0;
; #pragma unroll
;                 for (int bj = 0; bj < 2; ++bj) {
;                     const u32x4 hv = *(const u32x4*)(hb + off + bj * HALF);
;                     f32x4 r0, r1;
;                     r0[0] = bf_lo(hv.x); r0[1] = bf_hi(hv.x); r0[2] = bf_lo(hv.y); r0[3] = bf_hi(hv.y); r1[0] = bf_lo(hv.z); r1[1] = bf_hi(hv.z); r1[2] = bf_lo(hv.w); r1[3] = bf_hi(hv.w);
;                     *(f32x4*)(out + off + bj * HALF) = r0 * alpha + acc[ai][bj][m][0] * s;
;                     *(f32x4*)(out + off + bj * HALF + 4) = r1 * alpha + acc[ai][bj][m][1] * s;
;                 }
;                 if (m == 3) asm volatile("" ::: "memory");
;             }
;     }
	v_lshlrev_b32_e32 v156, 16, v204
	v_and_b32_e32 v157, 0xffff0000, v204
	v_lshlrev_b32_e32 v204, 16, v205
	v_and_b32_e32 v205, 0xffff0000, v205
	v_lshlrev_b32_e32 v158, 16, v206
	v_and_b32_e32 v159, 0xffff0000, v206
	v_lshlrev_b32_e32 v206, 16, v207
	v_and_b32_e32 v207, 0xffff0000, v207
	v_pk_fma_f32 v[38:39], v[204:205], s[12:13], v[38:39] op_sel_hi:[1,0,1]
	v_pk_fma_f32 v[36:37], v[156:157], s[12:13], v[36:37] op_sel_hi:[1,0,1]
	v_pk_fma_f32 v[34:35], v[206:207], s[12:13], v[34:35] op_sel_hi:[1,0,1]
	v_pk_fma_f32 v[32:33], v[158:159], s[12:13], v[32:33] op_sel_hi:[1,0,1]
	global_store_dwordx4 v[154:155], v[36:39], off offset:512
	global_store_dwordx4 v[154:155], v[32:35], off offset:528
	v_lshl_add_u64 v[152:153], v[234:235], 2, s[2:3]
	s_waitcnt vmcnt(27)
	v_lshlrev_b32_e32 v156, 16, v208
	v_and_b32_e32 v157, 0xffff0000, v208
	v_lshlrev_b32_e32 v208, 16, v209
	v_and_b32_e32 v209, 0xffff0000, v209
	v_lshlrev_b32_e32 v158, 16, v210
	v_and_b32_e32 v159, 0xffff0000, v210
	v_lshlrev_b32_e32 v210, 16, v211
	v_and_b32_e32 v211, 0xffff0000, v211
	v_pk_fma_f32 v[30:31], v[208:209], s[12:13], v[30:31] op_sel_hi:[1,0,1]
	v_pk_fma_f32 v[28:29], v[156:157], s[12:13], v[28:29] op_sel_hi:[1,0,1]
	v_pk_fma_f32 v[26:27], v[210:211], s[12:13], v[26:27] op_sel_hi:[1,0,1]
	v_pk_fma_f32 v[24:25], v[158:159], s[12:13], v[24:25] op_sel_hi:[1,0,1]
	global_store_dwordx4 v[152:153], v[28:31], off
	global_store_dwordx4 v[152:153], v[24:27], off offset:16
	s_waitcnt vmcnt(28)
	v_lshlrev_b32_e32 v156, 16, v212
	v_and_b32_e32 v157, 0xffff0000, v212
	v_lshlrev_b32_e32 v212, 16, v213
	v_and_b32_e32 v213, 0xffff0000, v213
	v_lshlrev_b32_e32 v158, 16, v214
	v_and_b32_e32 v159, 0xffff0000, v214
	v_lshlrev_b32_e32 v214, 16, v215
	v_and_b32_e32 v215, 0xffff0000, v215
	v_pk_fma_f32 v[22:23], v[212:213], s[12:13], v[22:23] op_sel_hi:[1,0,1]
	v_pk_fma_f32 v[20:21], v[156:157], s[12:13], v[20:21] op_sel_hi:[1,0,1]
	v_pk_fma_f32 v[18:19], v[214:215], s[12:13], v[18:19] op_sel_hi:[1,0,1]
	v_pk_fma_f32 v[16:17], v[158:159], s[12:13], v[16:17] op_sel_hi:[1,0,1]
	global_store_dwordx4 v[152:153], v[20:23], off offset:512
	global_store_dwordx4 v[152:153], v[16:19], off offset:528
	v_lshl_add_u64 v[154:155], v[236:237], 2, s[2:3]
	s_waitcnt vmcnt(29)
	v_lshlrev_b32_e32 v156, 16, v216
	v_and_b32_e32 v157, 0xffff0000, v216
	v_lshlrev_b32_e32 v216, 16, v217
	v_and_b32_e32 v217, 0xffff0000, v217
	v_lshlrev_b32_e32 v158, 16, v218
	v_and_b32_e32 v159, 0xffff0000, v218
	v_lshlrev_b32_e32 v218, 16, v219
	v_and_b32_e32 v219, 0xffff0000, v219
	v_pk_fma_f32 v[14:15], v[216:217], s[12:13], v[14:15] op_sel_hi:[1,0,1]
	v_pk_fma_f32 v[12:13], v[156:157], s[12:13], v[12:13] op_sel_hi:[1,0,1]
	v_pk_fma_f32 v[10:11], v[218:219], s[12:13], v[10:11] op_sel_hi:[1,0,1]
	v_pk_fma_f32 v[8:9], v[158:159], s[12:13], v[8:9] op_sel_hi:[1,0,1]
	global_store_dwordx4 v[154:155], v[12:15], off
	global_store_dwordx4 v[154:155], v[8:11], off offset:16
	s_waitcnt vmcnt(30)
	v_lshlrev_b32_e32 v156, 16, v220
	v_and_b32_e32 v157, 0xffff0000, v220
	v_lshlrev_b32_e32 v220, 16, v221
	v_and_b32_e32 v221, 0xffff0000, v221
	v_lshlrev_b32_e32 v158, 16, v222
	v_and_b32_e32 v159, 0xffff0000, v222
	v_lshlrev_b32_e32 v222, 16, v223
	v_and_b32_e32 v223, 0xffff0000, v223
	v_pk_fma_f32 v[6:7], v[220:221], s[12:13], v[6:7] op_sel_hi:[1,0,1]
	v_pk_fma_f32 v[4:5], v[156:157], s[12:13], v[4:5] op_sel_hi:[1,0,1]
	v_pk_fma_f32 v[2:3], v[222:223], s[12:13], v[2:3] op_sel_hi:[1,0,1]
	v_pk_fma_f32 v[0:1], v[158:159], s[12:13], v[0:1] op_sel_hi:[1,0,1]
	global_store_dwordx4 v[154:155], v[4:7], off offset:512
	global_store_dwordx4 v[154:155], v[0:3], off offset:528
	s_cbranch_vccnz .LBB0_773
	s_andn2_b64 vcc, exec, s[4:5]
	s_cbranch_vccnz .LBB0_772
	s_barrier
	s_branch .LBB0_772

; __device__ __forceinline__ float bf_lo(unsigned u) { return __uint_as_float(u << 16); }
; __device__ __forceinline__ float bf_hi(unsigned u) { return __uint_as_float(u & 0xffff0000u); }
;     __device__ __forceinline__ void operator()(AccRef acc, const Unit& u, int wr, int wc, int fr, int fq) const {
;         const int row0 = u.pm * BM + wr * 64 + fr, col0 = u.pn * BM + wc * 32 + 8 * fq;
; #pragma unroll
;         for (int ai = 0; ai < 2; ++ai)
; #pragma unroll
;             for (int m = 0; m < 4; ++m) {
;                 const size_t off = (size_t)(row0 + ai * HALF + m * 16) * D + col0;
; #pragma unroll
;                 for (int bj = 0; bj < 2; ++bj) {
;                     const u32x4 hv = *(const u32x4*)(hb + off + bj * HALF);
;                     f32x4 r0, r1;
;                     r0[0] = bf_lo(hv.x); r0[1] = bf_hi(hv.x); r0[2] = bf_lo(hv.y); r0[3] = bf_hi(hv.y); r1[0] = bf_lo(hv.z); r1[1] = bf_hi(hv.z); r1[2] = bf_lo(hv.w); r1[3] = bf_hi(hv.w);
;                     *(f32x4*)(out + off + bj * HALF) = r0 * alpha + acc[ai][bj][m][0] * s;
;                     *(f32x4*)(out + off + bj * HALF + 4) = r1 * alpha + acc[ai][bj][m][1] * s;
;                 }
;                 if (m == 3) asm volatile("" ::: "memory");
;             }
;     }
.LBB0_964:
	v_mov_b32_e32 v144, v147
	v_mov_b32_e32 v145, v146
	s_lshl_b32 s34, s63, 8
	s_add_i32 s34, s34, s54
	v_add_u32_e32 v144, s34, v144
	s_lshl_b32 s34, s64, 8
	s_or_b32 s34, s34, s55
	v_lshl_add_u32 v152, v145, 3, s34
	v_ashrrev_i32_e32 v145, 31, v144
	v_ashrrev_i32_e32 v153, 31, v152
	v_lshlrev_b64 v[144:145], 11, v[144:145]
	v_lshl_add_u64 v[144:145], v[144:145], 0, v[152:153]
	s_and_b64 vcc, exec, s[0:1]
	s_mov_b64 s[0:1], -1
	v_lshl_add_u64 v[238:239], v[144:145], 1, s[8:9]
	global_load_dwordx4 v[160:163], v[238:239], off
	global_load_dwordx4 v[164:167], v[238:239], off offset:256
	v_lshl_add_u64 v[224:225], v[144:145], 0, s[16:17]
	v_lshl_add_u64 v[240:241], v[224:225], 1, s[8:9]
	global_load_dwordx4 v[168:171], v[240:241], off
	global_load_dwordx4 v[172:175], v[240:241], off offset:256
	v_lshl_add_u64 v[226:227], v[144:145], 0, s[18:19]
	v_lshl_add_u64 v[242:243], v[226:227], 1, s[8:9]
	global_load_dwordx4 v[176:179], v[242:243], off
	global_load_dwordx4 v[180:183], v[242:243], off offset:256
	v_lshl_add_u64 v[228:229], v[144:145], 0, s[20:21]
	v_lshl_add_u64 v[244:245], v[228:229], 1, s[8:9]
	global_load_dwordx4 v[184:187], v[244:245], off
	global_load_dwordx4 v[188:191], v[244:245], off offset:256
	v_lshl_add_u64 v[230:231], v[144:145], 0, s[22:23]
	v_lshl_add_u64 v[246:247], v[230:231], 1, s[8:9]
	global_load_dwordx4 v[192:195], v[246:247], off
	global_load_dwordx4 v[196:199], v[246:247], off offset:256
	v_lshl_add_u64 v[232:233], v[144:145], 0, s[24:25]
	v_lshl_add_u64 v[248:249], v[232:233], 1, s[8:9]
	global_load_dwordx4 v[200:203], v[248:249], off
	global_load_dwordx4 v[204:207], v[248:249], off offset:256
	v_lshl_add_u64 v[234:235], v[144:145], 0, s[26:27]
	v_lshl_add_u64 v[250:251], v[234:235], 1, s[8:9]
	global_load_dwordx4 v[208:211], v[250:251], off
	global_load_dwordx4 v[212:215], v[250:251], off offset:256
	v_lshl_add_u64 v[236:237], v[144:145], 0, s[28:29]
	v_lshl_add_u64 v[252:253], v[236:237], 1, s[8:9]
	global_load_dwordx4 v[216:219], v[252:253], off
	global_load_dwordx4 v[220:223], v[252:253], off offset:256
	v_lshl_add_u64 v[152:153], v[144:145], 2, s[2:3]
	s_waitcnt vmcnt(15)
	v_lshlrev_b32_e32 v156, 16, v160
	v_and_b32_e32 v157, 0xffff0000, v160
	v_lshlrev_b32_e32 v160, 16, v161
	v_and_b32_e32 v161, 0xffff0000, v161
	v_lshlrev_b32_e32 v158, 16, v162
	v_and_b32_e32 v159, 0xffff0000, v162
	v_lshlrev_b32_e32 v162, 16, v163
	v_and_b32_e32 v163, 0xffff0000, v163
	v_pk_mul_f32 v[156:157], v[156:157], s[14:15] op_sel_hi:[1,0]
	v_pk_mul_f32 v[160:161], v[160:161], s[14:15] op_sel_hi:[1,0]
	v_pk_mul_f32 v[158:159], v[158:159], s[14:15] op_sel_hi:[1,0]
	v_pk_mul_f32 v[162:163], v[162:163], s[14:15] op_sel_hi:[1,0]
	v_pk_fma_f32 v[126:127], v[126:127], 0.5, v[160:161] op_sel_hi:[1,0,1]
	v_pk_fma_f32 v[124:125], v[124:125], 0.5, v[156:157] op_sel_hi:[1,0,1]
	v_pk_fma_f32 v[122:123], v[122:123], 0.5, v[162:163] op_sel_hi:[1,0,1]
	v_pk_fma_f32 v[120:121], v[120:121], 0.5, v[158:159] op_sel_hi:[1,0,1]
	global_store_dwordx4 v[152:153], v[124:127], off
	global_store_dwordx4 v[152:153], v[120:123], off offset:16
	s_waitcnt vmcnt(16)
	v_lshlrev_b32_e32 v156, 16, v164
	v_and_b32_e32 v157, 0xffff0000, v164
	v_lshlrev_b32_e32 v164, 16, v165
	v_and_b32_e32 v165, 0xffff0000, v165
	v_lshlrev_b32_e32 v158, 16, v166
	v_and_b32_e32 v159, 0xffff0000, v166
	v_lshlrev_b32_e32 v166, 16, v167
	v_and_b32_e32 v167, 0xffff0000, v167
	v_pk_mul_f32 v[156:157], v[156:157], s[14:15] op_sel_hi:[1,0]
	v_pk_mul_f32 v[164:165], v[164:165], s[14:15] op_sel_hi:[1,0]
	v_pk_mul_f32 v[158:159], v[158:159], s[14:15] op_sel_hi:[1,0]
	v_pk_mul_f32 v[166:167], v[166:167], s[14:15] op_sel_hi:[1,0]
	v_pk_fma_f32 v[118:119], v[118:119], 0.5, v[164:165] op_sel_hi:[1,0,1]
	v_pk_fma_f32 v[116:117], v[116:117], 0.5, v[156:157] op_sel_hi:[1,0,1]
	v_pk_fma_f32 v[114:115], v[114:115], 0.5, v[166:167] op_sel_hi:[1,0,1]
	v_pk_fma_f32 v[112:113], v[112:113], 0.5, v[158:159] op_sel_hi:[1,0,1]
	global_store_dwordx4 v[152:153], v[116:119], off offset:512
	global_store_dwordx4 v[152:153], v[112:115], off offset:528
	v_lshl_add_u64 v[154:155], v[224:225], 2, s[2:3]
	s_waitcnt vmcnt(17)
	v_lshlrev_b32_e32 v156, 16, v168
	v_and_b32_e32 v157, 0xffff0000, v168
	v_lshlrev_b32_e32 v168, 16, v169
	v_and_b32_e32 v169, 0xffff0000, v169
	v_lshlrev_b32_e32 v158, 16, v170
	v_and_b32_e32 v159, 0xffff0000, v170
	v_lshlrev_b32_e32 v170, 16, v171
	v_and_b32_e32 v171, 0xffff0000, v171
	v_pk_mul_f32 v[156:157], v[156:157], s[14:15] op_sel_hi:[1,0]
	v_pk_mul_f32 v[168:169], v[168:169], s[14:15] op_sel_hi:[1,0]
	v_pk_mul_f32 v[158:159], v[158:159], s[14:15] op_sel_hi:[1,0]
	v_pk_mul_f32 v[170:171], v[170:171], s[14:15] op_sel_hi:[1,0]
	v_pk_fma_f32 v[110:111], v[110:111], 0.5, v[168:169] op_sel_hi:[1,0,1]
	v_pk_fma_f32 v[108:109], v[108:109], 0.5, v[156:157] op_sel_hi:[1,0,1]
	v_pk_fma_f32 v[106:107], v[106:107], 0.5, v[170:171] op_sel_hi:[1,0,1]
	v_pk_fma_f32 v[104:105], v[104:105], 0.5, v[158:159] op_sel_hi:[1,0,1]
	global_store_dwordx4 v[154:155], v[108:111], off
	global_store_dwordx4 v[154:155], v[104:107], off offset:16
	s_waitcnt vmcnt(18)
	v_lshlrev_b32_e32 v156, 16, v172
	v_and_b32_e32 v157, 0xffff0000, v172
	v_lshlrev_b32_e32 v172, 16, v173
	v_and_b32_e32 v173, 0xffff0000, v173
	v_lshlrev_b32_e32 v158, 16, v174
	v_and_b32_e32 v159, 0xffff0000, v174
	v_lshlrev_b32_e32 v174, 16, v175
	v_and_b32_e32 v175, 0xffff0000, v175
	v_pk_mul_f32 v[156:157], v[156:157], s[14:15] op_sel_hi:[1,0]
	v_pk_mul_f32 v[172:173], v[172:173], s[14:15] op_sel_hi:[1,0]
	v_pk_mul_f32 v[158:159], v[158:159], s[14:15] op_sel_hi:[1,0]
	v_pk_mul_f32 v[174:175], v[174:175], s[14:15] op_sel_hi:[1,0]
	v_pk_fma_f32 v[102:103], v[102:103], 0.5, v[172:173] op_sel_hi:[1,0,1]
	v_pk_fma_f32 v[100:101], v[100:101], 0.5, v[156:157] op_sel_hi:[1,0,1]
	v_pk_fma_f32 v[98:99], v[98:99], 0.5, v[174:175] op_sel_hi:[1,0,1]
	v_pk_fma_f32 v[96:97], v[96:97], 0.5, v[158:159] op_sel_hi:[1,0,1]
	global_store_dwordx4 v[154:155], v[100:103], off offset:512
	global_store_dwordx4 v[154:155], v[96:99], off offset:528
	v_lshl_add_u64 v[152:153], v[226:227], 2, s[2:3]
	s_waitcnt vmcnt(19)
; __device__ __forceinline__ float bf_lo(unsigned u) { return __uint_as_float(u << 16); }
; __device__ __forceinline__ float bf_hi(unsigned u) { return __uint_as_float(u & 0xffff0000u); }
;     __device__ __forceinline__ void operator()(AccRef acc, const Unit& u, int wr, int wc, int fr, int fq) const {
;         const int row0 = u.pm * BM + wr * 64 + fr, col0 = u.pn * BM + wc * 32 + 8 * fq;
; #pragma unroll
;         for (int ai = 0; ai < 2; ++ai)
; #pragma unroll
;             for (int m = 0; m < 4; ++m) {
;                 const size_t off = (size_t)(row0 + ai * HALF + m * 16) * D + col0;
; #pragma unroll
;                 for (int bj = 0; bj < 2; ++bj) {
;                     const u32x4 hv = *(const u32x4*)(hb + off + bj * HALF);
;                     f32x4 r0, r1;
;                     r0[0] = bf_lo(hv.x); r0[1] = bf_hi(hv.x); r0[2] = bf_lo(hv.y); r0[3] = bf_hi(hv.y); r1[0] = bf_lo(hv.z); r1[1] = bf_hi(hv.z); r1[2] = bf_lo(hv.w); r1[3] = bf_hi(hv.w);
;                     *(f32x4*)(out + off + bj * HALF) = r0 * alpha + acc[ai][bj][m][0] * s;
;                     *(f32x4*)(out + off + bj * HALF + 4) = r1 * alpha + acc[ai][bj][m][1] * s;
;                 }
;                 if (m == 3) asm volatile("" ::: "memory");
;             }
;     }
	v_lshlrev_b32_e32 v156, 16, v176
	v_and_b32_e32 v157, 0xffff0000, v176
	v_lshlrev_b32_e32 v176, 16, v177
	v_and_b32_e32 v177, 0xffff0000, v177
	v_lshlrev_b32_e32 v158, 16, v178
	v_and_b32_e32 v159, 0xffff0000, v178
	v_lshlrev_b32_e32 v178, 16, v179
	v_and_b32_e32 v179, 0xffff0000, v179
	v_pk_mul_f32 v[156:157], v[156:157], s[14:15] op_sel_hi:[1,0]
	v_pk_mul_f32 v[176:177], v[176:177], s[14:15] op_sel_hi:[1,0]
	v_pk_mul_f32 v[158:159], v[158:159], s[14:15] op_sel_hi:[1,0]
	v_pk_mul_f32 v[178:179], v[178:179], s[14:15] op_sel_hi:[1,0]
	v_pk_fma_f32 v[94:95], v[94:95], 0.5, v[176:177] op_sel_hi:[1,0,1]
	v_pk_fma_f32 v[92:93], v[92:93], 0.5, v[156:157] op_sel_hi:[1,0,1]
	v_pk_fma_f32 v[90:91], v[90:91], 0.5, v[178:179] op_sel_hi:[1,0,1]
	v_pk_fma_f32 v[88:89], v[88:89], 0.5, v[158:159] op_sel_hi:[1,0,1]
	global_store_dwordx4 v[152:153], v[92:95], off
	global_store_dwordx4 v[152:153], v[88:91], off offset:16
	s_waitcnt vmcnt(20)
	v_lshlrev_b32_e32 v156, 16, v180
	v_and_b32_e32 v157, 0xffff0000, v180
	v_lshlrev_b32_e32 v180, 16, v181
	v_and_b32_e32 v181, 0xffff0000, v181
	v_lshlrev_b32_e32 v158, 16, v182
	v_and_b32_e32 v159, 0xffff0000, v182
	v_lshlrev_b32_e32 v182, 16, v183
	v_and_b32_e32 v183, 0xffff0000, v183
	v_pk_mul_f32 v[156:157], v[156:157], s[14:15] op_sel_hi:[1,0]
	v_pk_mul_f32 v[180:181], v[180:181], s[14:15] op_sel_hi:[1,0]
	v_pk_mul_f32 v[158:159], v[158:159], s[14:15] op_sel_hi:[1,0]
	v_pk_mul_f32 v[182:183], v[182:183], s[14:15] op_sel_hi:[1,0]
	v_pk_fma_f32 v[86:87], v[86:87], 0.5, v[180:181] op_sel_hi:[1,0,1]
	v_pk_fma_f32 v[84:85], v[84:85], 0.5, v[156:157] op_sel_hi:[1,0,1]
	v_pk_fma_f32 v[82:83], v[82:83], 0.5, v[182:183] op_sel_hi:[1,0,1]
	v_pk_fma_f32 v[80:81], v[80:81], 0.5, v[158:159] op_sel_hi:[1,0,1]
	global_store_dwordx4 v[152:153], v[84:87], off offset:512
	global_store_dwordx4 v[152:153], v[80:83], off offset:528
	v_lshl_add_u64 v[154:155], v[228:229], 2, s[2:3]
	s_waitcnt vmcnt(21)
	v_lshlrev_b32_e32 v156, 16, v184
	v_and_b32_e32 v157, 0xffff0000, v184
	v_lshlrev_b32_e32 v184, 16, v185
	v_and_b32_e32 v185, 0xffff0000, v185
	v_lshlrev_b32_e32 v158, 16, v186
	v_and_b32_e32 v159, 0xffff0000, v186
	v_lshlrev_b32_e32 v186, 16, v187
	v_and_b32_e32 v187, 0xffff0000, v187
	v_pk_mul_f32 v[156:157], v[156:157], s[14:15] op_sel_hi:[1,0]
	v_pk_mul_f32 v[184:185], v[184:185], s[14:15] op_sel_hi:[1,0]
	v_pk_mul_f32 v[158:159], v[158:159], s[14:15] op_sel_hi:[1,0]
	v_pk_mul_f32 v[186:187], v[186:187], s[14:15] op_sel_hi:[1,0]
	v_pk_fma_f32 v[78:79], v[78:79], 0.5, v[184:185] op_sel_hi:[1,0,1]
	v_pk_fma_f32 v[76:77], v[76:77], 0.5, v[156:157] op_sel_hi:[1,0,1]
	v_pk_fma_f32 v[74:75], v[74:75], 0.5, v[186:187] op_sel_hi:[1,0,1]
	v_pk_fma_f32 v[72:73], v[72:73], 0.5, v[158:159] op_sel_hi:[1,0,1]
	global_store_dwordx4 v[154:155], v[76:79], off
	global_store_dwordx4 v[154:155], v[72:75], off offset:16
	s_waitcnt vmcnt(22)
	v_lshlrev_b32_e32 v156, 16, v188
	v_and_b32_e32 v157, 0xffff0000, v188
	v_lshlrev_b32_e32 v188, 16, v189
	v_and_b32_e32 v189, 0xffff0000, v189
	v_lshlrev_b32_e32 v158, 16, v190
	v_and_b32_e32 v159, 0xffff0000, v190
	v_lshlrev_b32_e32 v190, 16, v191
	v_and_b32_e32 v191, 0xffff0000, v191
	v_pk_mul_f32 v[156:157], v[156:157], s[14:15] op_sel_hi:[1,0]
	v_pk_mul_f32 v[188:189], v[188:189], s[14:15] op_sel_hi:[1,0]
	v_pk_mul_f32 v[158:159], v[158:159], s[14:15] op_sel_hi:[1,0]
	v_pk_mul_f32 v[190:191], v[190:191], s[14:15] op_sel_hi:[1,0]
	v_pk_fma_f32 v[70:71], v[70:71], 0.5, v[188:189] op_sel_hi:[1,0,1]
	v_pk_fma_f32 v[68:69], v[68:69], 0.5, v[156:157] op_sel_hi:[1,0,1]
	v_pk_fma_f32 v[66:67], v[66:67], 0.5, v[190:191] op_sel_hi:[1,0,1]
	v_pk_fma_f32 v[64:65], v[64:65], 0.5, v[158:159] op_sel_hi:[1,0,1]
	global_store_dwordx4 v[154:155], v[68:71], off offset:512
	global_store_dwordx4 v[154:155], v[64:67], off offset:528
	v_lshl_add_u64 v[152:153], v[230:231], 2, s[2:3]
	s_waitcnt vmcnt(23)
	v_lshlrev_b32_e32 v156, 16, v192
	v_and_b32_e32 v157, 0xffff0000, v192
	v_lshlrev_b32_e32 v192, 16, v193
	v_and_b32_e32 v193, 0xffff0000, v193
	v_lshlrev_b32_e32 v158, 16, v194
	v_and_b32_e32 v159, 0xffff0000, v194
	v_lshlrev_b32_e32 v194, 16, v195
	v_and_b32_e32 v195, 0xffff0000, v195
	v_pk_mul_f32 v[156:157], v[156:157], s[14:15] op_sel_hi:[1,0]
	v_pk_mul_f32 v[192:193], v[192:193], s[14:15] op_sel_hi:[1,0]
	v_pk_mul_f32 v[158:159], v[158:159], s[14:15] op_sel_hi:[1,0]
	v_pk_mul_f32 v[194:195], v[194:195], s[14:15] op_sel_hi:[1,0]
	v_pk_fma_f32 v[62:63], v[62:63], 0.5, v[192:193] op_sel_hi:[1,0,1]
	v_pk_fma_f32 v[60:61], v[60:61], 0.5, v[156:157] op_sel_hi:[1,0,1]
	v_pk_fma_f32 v[58:59], v[58:59], 0.5, v[194:195] op_sel_hi:[1,0,1]
	v_pk_fma_f32 v[56:57], v[56:57], 0.5, v[158:159] op_sel_hi:[1,0,1]
	global_store_dwordx4 v[152:153], v[60:63], off
	global_store_dwordx4 v[152:153], v[56:59], off offset:16
	s_waitcnt vmcnt(24)
	v_lshlrev_b32_e32 v156, 16, v196
	v_and_b32_e32 v157, 0xffff0000, v196
	v_lshlrev_b32_e32 v196, 16, v197
	v_and_b32_e32 v197, 0xffff0000, v197
	v_lshlrev_b32_e32 v158, 16, v198
	v_and_b32_e32 v159, 0xffff0000, v198
	v_lshlrev_b32_e32 v198, 16, v199
	v_and_b32_e32 v199, 0xffff0000, v199
	v_pk_mul_f32 v[156:157], v[156:157], s[14:15] op_sel_hi:[1,0]
	v_pk_mul_f32 v[196:197], v[196:197], s[14:15] op_sel_hi:[1,0]
	v_pk_mul_f32 v[158:159], v[158:159], s[14:15] op_sel_hi:[1,0]
	v_pk_mul_f32 v[198:199], v[198:199], s[14:15] op_sel_hi:[1,0]
	v_pk_fma_f32 v[54:55], v[54:55], 0.5, v[196:197] op_sel_hi:[1,0,1]
	v_pk_fma_f32 v[52:53], v[52:53], 0.5, v[156:157] op_sel_hi:[1,0,1]
	v_pk_fma_f32 v[50:51], v[50:51], 0.5, v[198:199] op_sel_hi:[1,0,1]
	v_pk_fma_f32 v[48:49], v[48:49], 0.5, v[158:159] op_sel_hi:[1,0,1]
	global_store_dwordx4 v[152:153], v[52:55], off offset:512
	global_store_dwordx4 v[152:153], v[48:51], off offset:528
	v_lshl_add_u64 v[154:155], v[232:233], 2, s[2:3]
	s_waitcnt vmcnt(25)
; __device__ __forceinline__ float bf_lo(unsigned u) { return __uint_as_float(u << 16); }
; __device__ __forceinline__ float bf_hi(unsigned u) { return __uint_as_float(u & 0xffff0000u); }
; #define PG8_BAR __builtin_amdgcn_s_barrier()
; template <class Epi>
; __device__ __forceinline__ void gemm_phase(ldsp lds, const Gemm g, const StaticOrder& S, const Epi& E, int wave0) {
;     ...
;         if (!has_next) break;
; #pragma unroll
;         for (int a = 0; a < 2; ++a)
; #pragma unroll
;             for (int b = 0; b < 2; ++b)
; #pragma unroll
;                 for (int m = 0; m < 4; ++m)
; #pragma unroll
;                     for (int n = 0; n < 2; ++n) acc[a][b][m][n] = (f32x4){0.f, 0.f, 0.f, 0.f};
;         cur = nxt; cA = nA; cB = nB; ++ui;
;         if (wr == 1) PG8_BAR;
;     __device__ __forceinline__ void operator()(AccRef acc, const Unit& u, int wr, int wc, int fr, int fq) const {
;         const int row0 = u.pm * BM + wr * 64 + fr, col0 = u.pn * BM + wc * 32 + 8 * fq;
; #pragma unroll
;         for (int ai = 0; ai < 2; ++ai)
; #pragma unroll
;             for (int m = 0; m < 4; ++m) {
;                 const size_t off = (size_t)(row0 + ai * HALF + m * 16) * D + col0;
; #pragma unroll
;                 for (int bj = 0; bj < 2; ++bj) {
;                     const u32x4 hv = *(const u32x4*)(hb + off + bj * HALF);
;                     f32x4 r0, r1;
;                     r0[0] = bf_lo(hv.x); r0[1] = bf_hi(hv.x); r0[2] = bf_lo(hv.y); r0[3] = bf_hi(hv.y); r1[0] = bf_lo(hv.z); r1[1] = bf_hi(hv.z); r1[2] = bf_lo(hv.w); r1[3] = bf_hi(hv.w);
;                     *(f32x4*)(out + off + bj * HALF) = r0 * alpha + acc[ai][bj][m][0] * s;
;                     *(f32x4*)(out + off + bj * HALF + 4) = r1 * alpha + acc[ai][bj][m][1] * s;
;                 }
;                 if (m == 3) asm volatile("" ::: "memory");
;             }
;     }
	v_lshlrev_b32_e32 v156, 16, v200
	v_and_b32_e32 v157, 0xffff0000, v200
	v_lshlrev_b32_e32 v200, 16, v201
	v_and_b32_e32 v201, 0xffff0000, v201
	v_lshlrev_b32_e32 v158, 16, v202
	v_and_b32_e32 v159, 0xffff0000, v202
	v_lshlrev_b32_e32 v202, 16, v203
	v_and_b32_e32 v203, 0xffff0000, v203
	v_pk_mul_f32 v[156:157], v[156:157], s[14:15] op_sel_hi:[1,0]
	v_pk_mul_f32 v[200:201], v[200:201], s[14:15] op_sel_hi:[1,0]
	v_pk_mul_f32 v[158:159], v[158:159], s[14:15] op_sel_hi:[1,0]
	v_pk_mul_f32 v[202:203], v[202:203], s[14:15] op_sel_hi:[1,0]
	v_pk_fma_f32 v[46:47], v[46:47], 0.5, v[200:201] op_sel_hi:[1,0,1]
	v_pk_fma_f32 v[44:45], v[44:45], 0.5, v[156:157] op_sel_hi:[1,0,1]
	v_pk_fma_f32 v[42:43], v[42:43], 0.5, v[202:203] op_sel_hi:[1,0,1]
	v_pk_fma_f32 v[40:41], v[40:41], 0.5, v[158:159] op_sel_hi:[1,0,1]
	global_store_dwordx4 v[154:155], v[44:47], off
	global_store_dwordx4 v[154:155], v[40:43], off offset:16
	s_waitcnt vmcnt(26)
	v_lshlrev_b32_e32 v156, 16, v204
	v_and_b32_e32 v157, 0xffff0000, v204
	v_lshlrev_b32_e32 v204, 16, v205
	v_and_b32_e32 v205, 0xffff0000, v205
	v_lshlrev_b32_e32 v158, 16, v206
	v_and_b32_e32 v159, 0xffff0000, v206
	v_lshlrev_b32_e32 v206, 16, v207
	v_and_b32_e32 v207, 0xffff0000, v207
	v_pk_mul_f32 v[156:157], v[156:157], s[14:15] op_sel_hi:[1,0]
	v_pk_mul_f32 v[204:205], v[204:205], s[14:15] op_sel_hi:[1,0]
	v_pk_mul_f32 v[158:159], v[158:159], s[14:15] op_sel_hi:[1,0]
	v_pk_mul_f32 v[206:207], v[206:207], s[14:15] op_sel_hi:[1,0]
	v_pk_fma_f32 v[38:39], v[38:39], 0.5, v[204:205] op_sel_hi:[1,0,1]
	v_pk_fma_f32 v[36:37], v[36:37], 0.5, v[156:157] op_sel_hi:[1,0,1]
	v_pk_fma_f32 v[34:35], v[34:35], 0.5, v[206:207] op_sel_hi:[1,0,1]
	v_pk_fma_f32 v[32:33], v[32:33], 0.5, v[158:159] op_sel_hi:[1,0,1]
	global_store_dwordx4 v[154:155], v[36:39], off offset:512
	global_store_dwordx4 v[154:155], v[32:35], off offset:528
	v_lshl_add_u64 v[152:153], v[234:235], 2, s[2:3]
	s_waitcnt vmcnt(27)
	v_lshlrev_b32_e32 v156, 16, v208
	v_and_b32_e32 v157, 0xffff0000, v208
	v_lshlrev_b32_e32 v208, 16, v209
	v_and_b32_e32 v209, 0xffff0000, v209
	v_lshlrev_b32_e32 v158, 16, v210
	v_and_b32_e32 v159, 0xffff0000, v210
	v_lshlrev_b32_e32 v210, 16, v211
	v_and_b32_e32 v211, 0xffff0000, v211
	v_pk_mul_f32 v[156:157], v[156:157], s[14:15] op_sel_hi:[1,0]
	v_pk_mul_f32 v[208:209], v[208:209], s[14:15] op_sel_hi:[1,0]
	v_pk_mul_f32 v[158:159], v[158:159], s[14:15] op_sel_hi:[1,0]
	v_pk_mul_f32 v[210:211], v[210:211], s[14:15] op_sel_hi:[1,0]
	v_pk_fma_f32 v[30:31], v[30:31], 0.5, v[208:209] op_sel_hi:[1,0,1]
	v_pk_fma_f32 v[28:29], v[28:29], 0.5, v[156:157] op_sel_hi:[1,0,1]
	v_pk_fma_f32 v[26:27], v[26:27], 0.5, v[210:211] op_sel_hi:[1,0,1]
	v_pk_fma_f32 v[24:25], v[24:25], 0.5, v[158:159] op_sel_hi:[1,0,1]
	global_store_dwordx4 v[152:153], v[28:31], off
	global_store_dwordx4 v[152:153], v[24:27], off offset:16
	s_waitcnt vmcnt(28)
	v_lshlrev_b32_e32 v156, 16, v212
	v_and_b32_e32 v157, 0xffff0000, v212
	v_lshlrev_b32_e32 v212, 16, v213
	v_and_b32_e32 v213, 0xffff0000, v213
	v_lshlrev_b32_e32 v158, 16, v214
	v_and_b32_e32 v159, 0xffff0000, v214
	v_lshlrev_b32_e32 v214, 16, v215
	v_and_b32_e32 v215, 0xffff0000, v215
	v_pk_mul_f32 v[156:157], v[156:157], s[14:15] op_sel_hi:[1,0]
	v_pk_mul_f32 v[212:213], v[212:213], s[14:15] op_sel_hi:[1,0]
	v_pk_mul_f32 v[158:159], v[158:159], s[14:15] op_sel_hi:[1,0]
	v_pk_mul_f32 v[214:215], v[214:215], s[14:15] op_sel_hi:[1,0]
	v_pk_fma_f32 v[22:23], v[22:23], 0.5, v[212:213] op_sel_hi:[1,0,1]
	v_pk_fma_f32 v[20:21], v[20:21], 0.5, v[156:157] op_sel_hi:[1,0,1]
	v_pk_fma_f32 v[18:19], v[18:19], 0.5, v[214:215] op_sel_hi:[1,0,1]
	v_pk_fma_f32 v[16:17], v[16:17], 0.5, v[158:159] op_sel_hi:[1,0,1]
	global_store_dwordx4 v[152:153], v[20:23], off offset:512
	global_store_dwordx4 v[152:153], v[16:19], off offset:528
	v_lshl_add_u64 v[154:155], v[236:237], 2, s[2:3]
	s_waitcnt vmcnt(29)
	v_lshlrev_b32_e32 v156, 16, v216
	v_and_b32_e32 v157, 0xffff0000, v216
	v_lshlrev_b32_e32 v216, 16, v217
	v_and_b32_e32 v217, 0xffff0000, v217
	v_lshlrev_b32_e32 v158, 16, v218
	v_and_b32_e32 v159, 0xffff0000, v218
	v_lshlrev_b32_e32 v218, 16, v219
	v_and_b32_e32 v219, 0xffff0000, v219
	v_pk_mul_f32 v[156:157], v[156:157], s[14:15] op_sel_hi:[1,0]
	v_pk_mul_f32 v[216:217], v[216:217], s[14:15] op_sel_hi:[1,0]
	v_pk_mul_f32 v[158:159], v[158:159], s[14:15] op_sel_hi:[1,0]
	v_pk_mul_f32 v[218:219], v[218:219], s[14:15] op_sel_hi:[1,0]
	v_pk_fma_f32 v[14:15], v[14:15], 0.5, v[216:217] op_sel_hi:[1,0,1]
	v_pk_fma_f32 v[12:13], v[12:13], 0.5, v[156:157] op_sel_hi:[1,0,1]
	v_pk_fma_f32 v[10:11], v[10:11], 0.5, v[218:219] op_sel_hi:[1,0,1]
	v_pk_fma_f32 v[8:9], v[8:9], 0.5, v[158:159] op_sel_hi:[1,0,1]
	global_store_dwordx4 v[154:155], v[12:15], off
	global_store_dwordx4 v[154:155], v[8:11], off offset:16
	s_waitcnt vmcnt(30)
	v_lshlrev_b32_e32 v156, 16, v220
	v_and_b32_e32 v157, 0xffff0000, v220
	v_lshlrev_b32_e32 v220, 16, v221
	v_and_b32_e32 v221, 0xffff0000, v221
	v_lshlrev_b32_e32 v158, 16, v222
	v_and_b32_e32 v159, 0xffff0000, v222
	v_lshlrev_b32_e32 v222, 16, v223
	v_and_b32_e32 v223, 0xffff0000, v223
	v_pk_mul_f32 v[156:157], v[156:157], s[14:15] op_sel_hi:[1,0]
	v_pk_mul_f32 v[220:221], v[220:221], s[14:15] op_sel_hi:[1,0]
	v_pk_mul_f32 v[158:159], v[158:159], s[14:15] op_sel_hi:[1,0]
	v_pk_mul_f32 v[222:223], v[222:223], s[14:15] op_sel_hi:[1,0]
	v_pk_fma_f32 v[6:7], v[6:7], 0.5, v[220:221] op_sel_hi:[1,0,1]
	v_pk_fma_f32 v[4:5], v[4:5], 0.5, v[156:157] op_sel_hi:[1,0,1]
	v_pk_fma_f32 v[2:3], v[2:3], 0.5, v[222:223] op_sel_hi:[1,0,1]
	v_pk_fma_f32 v[0:1], v[0:1], 0.5, v[158:159] op_sel_hi:[1,0,1]
	global_store_dwordx4 v[154:155], v[4:7], off offset:512
	global_store_dwordx4 v[154:155], v[0:3], off offset:528
	s_cbranch_vccnz .LBB0_949
	s_andn2_b64 vcc, exec, s[6:7]
	s_cbranch_vccnz .LBB0_948
	s_barrier
	s_branch .LBB0_948
